# g1_throttle_2us_with_lean_loader
# speedup vs baseline: 1.0132x; 1.0010x over previous
.LBB0_2357:
	s_or_b64 exec, exec, s[0:1]
	s_add_i32 s91, s42, s91
	s_cmpk_lt_i32 s91, 0xc00
	s_cbranch_scc0 .LBB0_2485
	s_sleep 64
